# MLA attention: QK ring prefetch, V loads hoisted to tile top, static prio for waves 4-7
# speedup vs baseline: 1.0029x; 1.0029x over previous
; template <int DQK, bool MLA, bool QREG = true>
; DI void attn_unit(LAS unsigned char* lds, const bf16_t* Q, int ldq, int nqv, const bf16_t* K1, int ldk1, const bf16_t* K2, const bf16_t* VT, int ldv,
;                   int ntiles, int lim, int nkeys, bf16_t* O, int ldo, int tid, int wid, int lane) {
;     constexpr int KS = DQK + 8, KBYTES = 64 * KS * 2, VBYTES = 128 * 136, BUF = KBYTES + VBYTES, KP = DQK / 64;
;     const int r = lane & 31, h = lane >> 5;
;     bf16x8 qf[QREG ? DQK / 16 : 1];
;     const bf16x8 zero8 = {0, 0, 0, 0, 0, 0, 0, 0};
;     const bool qok = (wid * 32 + r) < nqv; const bf16_t* qptr = Q + (size_t)(wid * 32 + r) * ldq + 8 * h;
;     if (QREG) {
; #pragma unroll
;       for (int s = 0; s < DQK / 16; ++s) qf[QREG ? s : 0] = qok ? *(const bf16x8*)(qptr + 16 * s) : zero8; }
;     ...
;     f32x16 o[4];
; #pragma unroll
;     for (int i = 0; i < 4; ++i)
; #pragma unroll
;         for (int j = 0; j < 16; ++j) o[i][j] = 0.f;
;     float mrun = -1e30f, lrun = 0.f;
;     u32x4 kreg[KP]; u32x2 vreg[4];
;     const unsigned kgo1 = (unsigned)((tid >> 3) * ldk1 + (tid & 7) * 8) * 2u;
;     const unsigned vgo = (unsigned)((tid >> 3) * ldv + (tid & 7) * 8) * 2u, vgs = (unsigned)ldv * 128u;
;     const unsigned klo = (unsigned)((tid >> 3) * (KS * 2) + (tid & 7) * 16), vlo = (unsigned)(KBYTES + (tid >> 3) * 136 + (tid & 7) * 16);
; __global__ void __launch_bounds__(512, 2) fwd_mega(Params P) {
;     ...
;                     attn_unit<192, true>(lds, WSB(WS_Q) + rowq * 1536 + hh * 192, 1536, 256, WSB(WS_KN) + (size_t)b * SEQ * 1024 + hh * 128, 1024, WSB(WS_KR) + (size_t)b * SEQ * 64,
;                                          WSB(WS_VT) + ((size_t)b * 1024 + hh * 128) * SEQ, SEQ, 4 * qb + 4, 4 * qb + (wid >> 1) + 1, 1 << 30,
;                                          WSB(WS_OM) + rowq * 1024 + hh * 128, 1024, tid, wid, lane);
.LBB0_1281:
	s_or_b64 exec, exec, s[6:7]
	v_readlane_b32 s8, v252, 0
	v_readlane_b32 s9, v252, 1
	s_waitcnt lgkmcnt(0)
	s_barrier
	s_load_dwordx2 s[6:7], s[8:9], 0xe8
	v_readlane_b32 s10, v252, 6
	v_mbcnt_lo_u32_b32 v219, -1, 0
	v_mbcnt_hi_u32_b32 v219, -1, v219
	s_nop 0
	v_and_b32_e32 v214, 31, v219
	v_add_u32_e32 v217, s10, v219
	v_readlane_b32 s10, v252, 33
	v_readlane_b32 s11, v252, 34
	v_ashrrev_i32_e32 v216, 5, v219
	s_andn2_b64 vcc, exec, s[10:11]
	v_ashrrev_i32_e32 v218, 3, v217
	v_or_b32_e32 v234, s86, v214
	v_lshlrev_b32_e32 v182, 3, v216
	v_lshlrev_b32_e32 v215, 4, v216
	v_mul_u32_u24_e32 v169, 0x88, v214
	s_cbranch_vccnz .LBB0_1327
	v_readlane_b32 s10, v252, 6
	s_cmpk_lt_u32 s10, 0x100
	s_cbranch_scc1 .Lmy_prio_skip0
	s_setprio 1
.Lmy_prio_skip0:
	s_waitcnt lgkmcnt(0)
	v_mov_b64_e32 v[2:3], s[6:7]
	s_movk_i32 s10, 0xc00
	v_mad_u64_u32 v[2:3], s[10:11], v234, s10, v[2:3]
	v_ashrrev_i32_e32 v183, 31, v182
	v_lshl_add_u64 v[2:3], v[182:183], 1, v[2:3]
	s_mov_b64 s[10:11], 0x156c2800
	v_lshl_add_u64 v[160:161], v[2:3], 0, s[10:11]
	v_lshlrev_b32_e32 v0, 4, v217
	s_movk_i32 s10, 0x190
	s_add_u32 s18, s6, 0x186c2800
	v_and_b32_e32 v4, 0x70, v0
	v_mul_lo_u32 v5, v218, s10
	v_lshl_add_u64 v[2:3], s[6:7], 0, v[0:1]
	s_mov_b64 s[10:11], 0x1c6c2800
	s_addc_u32 s19, s7, 0
	v_lshl_add_u64 v[166:167], v[2:3], 0, s[10:11]
	v_add3_u32 v168, 0, v5, v4
	s_movk_i32 s10, 0xfef8
	s_add_u32 s20, s6, 0x1a6c2800
	v_mad_u64_u32 v[170:171], s[10:11], v218, s10, v[168:169]
	s_addc_u32 s21, s7, 0
	s_mov_b64 s[10:11], 0x1c6c4800
	s_add_u32 s22, s6, 0x1e8c2800
	v_lshl_add_u64 v[172:173], v[0:1], 0, s[10:11]
	v_readlane_b32 s10, v252, 7
	s_addc_u32 s23, s7, 0
	v_lshl_or_b32 v162, v218, 11, v4
	v_lshl_or_b32 v164, v218, 12, v4
	v_mov_b32_e32 v163, v1
	v_mov_b32_e32 v165, v1
	v_mul_u32_u24_e32 v171, 0x190, v214
	s_mov_b32 s24, s10
	v_readlane_b32 s11, v252, 8
	s_branch .LBB0_1284

; #define LAS __attribute__((address_space(3)))
; #define ATT_LOADK(t) do { const char* k1_ = (const char*)K1 + (size_t)(t) * 128 * ldk1; const char* k2_ = (const char*)K2 + (size_t)(t) * 8192; \
;     _Pragma("unroll") for (int j = 0; j < KP; ++j) { \
;         if (MLA && j == 2) kreg[j] = *(const u32x4*)(k2_ + ((unsigned)tid << 4)); else kreg[j] = *(const u32x4*)(k1_ + kgo1 + j * 128); } } while (0)
; #define ATT_LOADV(t) do { const char* v_ = (const char*)VT + (size_t)(t) * 128; \
;     _Pragma("unroll") for (int j = 0; j < 2; ++j) { const u32x4 w = *(const u32x4*)(v_ + vgo + j * vgs); \
;         vreg[2 * j] = (u32x2){w.x, w.y}; vreg[2 * j + 1] = (u32x2){w.z, w.w}; } } while (0)
; #define ATT_STOREK(buf) do { LAS unsigned char* kb_ = lds + (buf) * BUF + klo; \
;     _Pragma("unroll") for (int j = 0; j < KP; ++j) *(LAS u32x4*)(kb_ + j * 128) = kreg[j]; } while (0)
; template <int DQK, bool MLA, bool QREG = true>
; DI void attn_unit(LAS unsigned char* lds, const bf16_t* Q, int ldq, int nqv, const bf16_t* K1, int ldk1, const bf16_t* K2, const bf16_t* VT, int ldv,
;                   int ntiles, int lim, int nkeys, bf16_t* O, int ldo, int tid, int wid, int lane) {
;     ...
;     for (int t = 0; t < ntiles; ++t) {
;         const int buf = t & 1; const bool more = t + 1 < ntiles;
;         const LAS unsigned char* kb = lds + buf * BUF; const LAS unsigned char* vb = kb + KBYTES;
;         f32x16 s0_, s1_;
;         if (more) ATT_LOADK(t + 1);
;         if (t < lim) { ATT_QK() }
;         if (more) { ATT_STOREK(buf ^ 1); ATT_LOADV(t + 1); }
.LBB0_1314:
	v_lshl_add_u64 v[198:199], s[6:7], 0, v[206:207]
	v_add_co_u32_e32 v198, vcc, 0x186e2000, v198
	v_lshl_add_u64 v[212:213], s[6:7], 0, v[208:209]
	s_nop 0
	v_addc_co_u32_e32 v199, vcc, 0, v199, vcc
	global_load_dwordx4 v[244:247], v[198:199], off offset:2176
	global_load_dwordx4 v[230:233], v[198:199], off offset:2048
	global_load_dwordx4 v[248:251], v[212:213], off
	v_lshl_add_u64 v[6:7], s[6:7], 0, v[210:211]
	v_add_co_u32_e32 v2, vcc, 0x1a6c2000, v6
	s_nop 1
	v_addc_co_u32_e32 v3, vcc, 0, v7, vcc
	v_add_co_u32_e32 v6, vcc, 0x1a702000, v6
	global_load_dwordx4 v[2:5], v[2:3], off offset:2176
	s_nop 0
	v_addc_co_u32_e32 v7, vcc, 0, v7, vcc
	global_load_dwordx4 v[6:9], v[6:7], off offset:2176
	s_and_b32 s34, s31, 1
	s_mul_i32 s16, s34, 0xa800
	s_add_i32 s35, s16, 0
	s_cmp_le_u32 s31, s29
	s_cselect_b64 s[16:17], -1, 0
	s_cmp_gt_u32 s31, s29
	s_cbranch_scc1 .LBB0_1316
	v_add3_u32 v0, s35, v171, v215
	ds_read_b128 v[80:83], v0
	ds_read_b128 v[96:99], v0 offset:12800
	ds_read_b128 v[186:189], v0 offset:32
	ds_read_b128 v[190:193], v0 offset:12832
	ds_read_b128 v[194:197], v0 offset:64
	ds_read_b128 v[236:239], v0 offset:12864
	ds_read_b128 v[240:243], v0 offset:96
	ds_read_b128 v[10:13], v0 offset:12896
	s_waitcnt lgkmcnt(7)
	v_mfma_f32_32x32x16_bf16 v[80:95], v[80:83], v[116:119], 0
	s_waitcnt lgkmcnt(6)
	v_mfma_f32_32x32x16_bf16 v[96:111], v[96:99], v[116:119], 0
	s_waitcnt lgkmcnt(5)
	v_mfma_f32_32x32x16_bf16 v[80:95], v[186:189], v[112:115], v[80:95]
	ds_read_b128 v[186:189], v0 offset:128
	s_waitcnt lgkmcnt(5)
	v_mfma_f32_32x32x16_bf16 v[96:111], v[190:193], v[112:115], v[96:111]
	ds_read_b128 v[190:193], v0 offset:12928
	s_waitcnt lgkmcnt(5)
	v_mfma_f32_32x32x16_bf16 v[80:95], v[194:197], v[124:127], v[80:95]
	ds_read_b128 v[194:197], v0 offset:160
	s_waitcnt lgkmcnt(5)
	v_mfma_f32_32x32x16_bf16 v[96:111], v[236:239], v[124:127], v[96:111]
	ds_read_b128 v[236:239], v0 offset:12960
	s_waitcnt lgkmcnt(5)
	v_mfma_f32_32x32x16_bf16 v[80:95], v[240:243], v[120:123], v[80:95]
	ds_read_b128 v[240:243], v0 offset:192
	s_waitcnt lgkmcnt(5)
	v_mfma_f32_32x32x16_bf16 v[96:111], v[10:13], v[120:123], v[96:111]
	ds_read_b128 v[10:13], v0 offset:12992
	s_waitcnt lgkmcnt(5)
	v_mfma_f32_32x32x16_bf16 v[80:95], v[186:189], v[132:135], v[80:95]
	ds_read_b128 v[186:189], v0 offset:224
	s_waitcnt lgkmcnt(5)
	v_mfma_f32_32x32x16_bf16 v[96:111], v[190:193], v[132:135], v[96:111]
	ds_read_b128 v[190:193], v0 offset:13024
	s_waitcnt lgkmcnt(5)
	v_mfma_f32_32x32x16_bf16 v[80:95], v[194:197], v[128:131], v[80:95]
	ds_read_b128 v[194:197], v0 offset:256
	s_waitcnt lgkmcnt(5)
	v_mfma_f32_32x32x16_bf16 v[96:111], v[236:239], v[128:131], v[96:111]
	ds_read_b128 v[236:239], v0 offset:13056
	s_waitcnt lgkmcnt(5)
	v_mfma_f32_32x32x16_bf16 v[80:95], v[240:243], v[144:147], v[80:95]
	ds_read_b128 v[240:243], v0 offset:288
	s_waitcnt lgkmcnt(5)
	v_mfma_f32_32x32x16_bf16 v[96:111], v[10:13], v[144:147], v[96:111]
	ds_read_b128 v[10:13], v0 offset:13088
	s_waitcnt lgkmcnt(5)
	v_mfma_f32_32x32x16_bf16 v[80:95], v[186:189], v[136:139], v[80:95]
	ds_read_b128 v[186:189], v0 offset:320
	s_waitcnt lgkmcnt(5)
	v_mfma_f32_32x32x16_bf16 v[96:111], v[190:193], v[136:139], v[96:111]
	ds_read_b128 v[190:193], v0 offset:13120
	s_waitcnt lgkmcnt(5)
	v_mfma_f32_32x32x16_bf16 v[80:95], v[194:197], v[152:155], v[80:95]
	ds_read_b128 v[194:197], v0 offset:352
	s_waitcnt lgkmcnt(5)
	v_mfma_f32_32x32x16_bf16 v[96:111], v[236:239], v[152:155], v[96:111]
	ds_read_b128 v[236:239], v0 offset:13152
	s_waitcnt lgkmcnt(5)
	v_mfma_f32_32x32x16_bf16 v[80:95], v[240:243], v[148:151], v[80:95]
	s_waitcnt lgkmcnt(4)
	v_mfma_f32_32x32x16_bf16 v[96:111], v[10:13], v[148:151], v[96:111]
	s_waitcnt lgkmcnt(3)
	v_mfma_f32_32x32x16_bf16 v[80:95], v[186:189], v[156:159], v[80:95]
	s_waitcnt lgkmcnt(2)
	v_mfma_f32_32x32x16_bf16 v[96:111], v[190:193], v[156:159], v[96:111]
	s_waitcnt lgkmcnt(1)
	v_mfma_f32_32x32x16_bf16 v[80:95], v[194:197], v[140:143], v[80:95]
	s_waitcnt lgkmcnt(0)
	v_mfma_f32_32x32x16_bf16 v[96:111], v[236:239], v[140:143], v[96:111]
.LBB0_1316:
	s_xor_b32 s34, s34, 1
	s_mul_i32 s34, s34, 0xa800
	v_add_u32_e32 v0, s34, v168
	s_waitcnt vmcnt(3)
	ds_write_b128 v0, v[230:233]
	ds_write_b128 v0, v[244:247] offset:128
	s_waitcnt vmcnt(2)
	ds_write_b128 v0, v[248:251] offset:256
	s_andn2_b64 vcc, exec, s[16:17]
	s_cbranch_vccnz .LBB0_1313
	s_nop 15
	v_max3_f32 v0, v80, v81, v82
	v_max3_f32 v0, v0, v83, v84
	v_max3_f32 v0, v0, v85, v86
	v_max3_f32 v0, v0, v87, v88
	v_max3_f32 v0, v0, v89, v90
	v_max3_f32 v0, v0, v91, v92
	v_max3_f32 v0, v0, v93, v94
	v_max_f32 v0, v0, v95
	s_nop 15
	v_max3_f32 v10, v96, v97, v98
	v_max3_f32 v10, v10, v99, v100
	v_max3_f32 v10, v10, v101, v102
	v_max3_f32 v10, v10, v103, v104
	v_max3_f32 v10, v10, v105, v106
	v_max3_f32 v10, v10, v107, v108
	v_max3_f32 v10, v10, v109, v110
	v_max_f32 v10, v10, v111
	s_nop 0
	v_max_f32_e32 v0, v0, v0
	v_max_f32_e32 v10, v10, v10
	v_max_f32_e32 v0, v0, v10
	v_mbcnt_hi_u32_b32 v10, -1, v220
	v_and_b32_e32 v12, 64, v10
	v_xor_b32_e32 v11, 32, v10
	v_add_u32_e32 v12, 64, v12
	v_cmp_lt_i32_e32 vcc, v11, v12
	s_nop 1
	v_cndmask_b32_e32 v10, v10, v11, vcc
	v_lshlrev_b32_e32 v10, 2, v10
	ds_bpermute_b32 v10, v10, v0
	s_waitcnt lgkmcnt(0)
	v_max_f32_e32 v10, v10, v10
	v_max_f32_e32 v0, v0, v10
	v_add_f32_e32 v10, 0x41000000, v235
	v_cmp_gt_f32_e32 vcc, v0, v10
	s_cbranch_vccz .LBB0_1312
	s_nop 0
	v_cndmask_b32_e32 v10, v235, v0, vcc
	v_sub_f32_e32 v0, v235, v10
	v_exp_f32_e32 v0, v0
	v_mov_b32_e32 v235, v10
	v_pk_mul_f32 v[78:79], v[78:79], v[0:1] op_sel_hi:[1,0]
	v_pk_mul_f32 v[76:77], v[76:77], v[0:1] op_sel_hi:[1,0]
	v_pk_mul_f32 v[74:75], v[74:75], v[0:1] op_sel_hi:[1,0]
	v_pk_mul_f32 v[72:73], v[72:73], v[0:1] op_sel_hi:[1,0]
	v_pk_mul_f32 v[70:71], v[70:71], v[0:1] op_sel_hi:[1,0]
	v_pk_mul_f32 v[68:69], v[68:69], v[0:1] op_sel_hi:[1,0]
	v_pk_mul_f32 v[66:67], v[66:67], v[0:1] op_sel_hi:[1,0]
	v_pk_mul_f32 v[64:65], v[64:65], v[0:1] op_sel_hi:[1,0]
	v_pk_mul_f32 v[62:63], v[62:63], v[0:1] op_sel_hi:[1,0]
	v_pk_mul_f32 v[60:61], v[60:61], v[0:1] op_sel_hi:[1,0]
	v_pk_mul_f32 v[58:59], v[58:59], v[0:1] op_sel_hi:[1,0]
	v_pk_mul_f32 v[56:57], v[56:57], v[0:1] op_sel_hi:[1,0]
	v_pk_mul_f32 v[54:55], v[54:55], v[0:1] op_sel_hi:[1,0]
	v_pk_mul_f32 v[52:53], v[52:53], v[0:1] op_sel_hi:[1,0]
	v_pk_mul_f32 v[50:51], v[50:51], v[0:1] op_sel_hi:[1,0]
	v_pk_mul_f32 v[48:49], v[48:49], v[0:1] op_sel_hi:[1,0]
	v_pk_mul_f32 v[46:47], v[46:47], v[0:1] op_sel_hi:[1,0]
	v_pk_mul_f32 v[44:45], v[44:45], v[0:1] op_sel_hi:[1,0]
	v_pk_mul_f32 v[42:43], v[42:43], v[0:1] op_sel_hi:[1,0]
	v_pk_mul_f32 v[40:41], v[40:41], v[0:1] op_sel_hi:[1,0]
	v_pk_mul_f32 v[38:39], v[38:39], v[0:1] op_sel_hi:[1,0]
	v_pk_mul_f32 v[36:37], v[36:37], v[0:1] op_sel_hi:[1,0]
	v_pk_mul_f32 v[34:35], v[34:35], v[0:1] op_sel_hi:[1,0]
	v_pk_mul_f32 v[32:33], v[32:33], v[0:1] op_sel_hi:[1,0]
	v_pk_mul_f32 v[30:31], v[30:31], v[0:1] op_sel_hi:[1,0]
	v_pk_mul_f32 v[28:29], v[28:29], v[0:1] op_sel_hi:[1,0]
	v_pk_mul_f32 v[26:27], v[26:27], v[0:1] op_sel_hi:[1,0]
	v_pk_mul_f32 v[24:25], v[24:25], v[0:1] op_sel_hi:[1,0]
	v_pk_mul_f32 v[22:23], v[22:23], v[0:1] op_sel_hi:[1,0]
	v_pk_mul_f32 v[20:21], v[20:21], v[0:1] op_sel_hi:[1,0]
	v_pk_mul_f32 v[18:19], v[18:19], v[0:1] op_sel_hi:[1,0]
	v_pk_mul_f32 v[16:17], v[16:17], v[0:1] op_sel_hi:[1,0]
	v_mul_f32_e32 v183, v183, v0
	s_branch .LBB0_1312

; #define LAS __attribute__((address_space(3)))
; DI void gm_unit(LAS unsigned char* lds, const bf16_t* Zrow0  , int nvalid, int gch, const bf16_t* Wsb, const float* bs, const float* gmg, const float* sv,
;                 bf16_t* OG  , int tid, int wid, int lane, bool loadW = true) {
;     LAS unsigned char* Wl = lds; LAS unsigned char* Vt = lds + 128 * 272;
;     if (loadW)
; #pragma unroll
;     for (int j = 0; j < 4; ++j) { const int p = tid + 512 * j, pr = p >> 4, c8 = p & 15; *(LAS u32x4*)(Wl + pr * 272 + c8 * 16) = *(const u32x4*)(Wsb + (size_t)gch * 16384 + pr * 128 + c8 * 8); }
; #pragma unroll
;     for (int j = 0; j < 4; ++j) {
;         const int p = tid + 512 * j, q = p & 127, cg = p >> 7;
;         u32x4 w = {0u, 0u, 0u, 0u}; float rs = 0.f;
;         if (q < nvalid) { w = *(const u32x4*)(Zrow0 + (size_t)q * NZ + ZV + gch * 128 + cg * 8); rs = rsqrtf(sv[q] * (1.0f / 1024.0f) + EPS); }
.LBB0_1371:
	s_setprio 0
	v_readlane_b32 s10, v252, 37
	v_readlane_b32 s11, v252, 38
	s_andn2_b64 vcc, exec, s[10:11]
	s_cbranch_vccnz .LBB0_1380
	v_and_b32_e32 v0, 0xf0, v208
	s_waitcnt lgkmcnt(0)
	v_lshl_add_u64 v[2:3], s[6:7], 0, v[0:1]
	v_add_u32_e32 v5, 0, v0
	v_add_u32_e32 v0, 0x200, v217
	s_add_u32 s18, s6, 0x7ec2800
	v_ashrrev_i32_e32 v6, 4, v0
	v_add_u32_e32 v0, 0x400, v217
	s_addc_u32 s19, s7, 0
	v_readlane_b32 s12, v254, 59
	v_ashrrev_i32_e32 v9, 4, v0
	v_add_u32_e32 v0, 0x600, v217
	v_readlane_b32 s13, v254, 60
	s_add_u32 s12, s6, s12
	v_ashrrev_i32_e32 v11, 4, v0
	v_and_b32_e32 v0, 0x7f, v217
	s_addc_u32 s13, s7, s13
	s_mov_b64 s[14:15], 0x2d20000
	v_lshl_add_u32 v13, v0, 1, 0
	v_mul_hi_u32_u24_e32 v29, 0x3600, v0
	v_mul_u32_u24_e32 v28, 0x3600, v0
	v_lshlrev_b32_e32 v0, 2, v0
	v_lshl_add_u64 v[18:19], v[2:3], 0, s[14:15]
	v_lshl_add_u64 v[2:3], s[12:13], 0, v[0:1]
	s_mov_b64 s[12:13], 0x2d60000
	s_load_dwordx2 s[10:11], s[8:9], 0x48
	s_nop 0
	s_load_dwordx2 s[8:9], s[8:9], 0x58
	v_lshl_add_u64 v[30:31], v[2:3], 0, s[12:13]
	v_lshlrev_b32_e32 v40, 2, v216
	v_readlane_b32 s12, v252, 39
	v_ashrrev_i32_e32 v4, 4, v217
	s_movk_i32 s14, 0x110
	v_add_u32_e32 v52, s12, v40
	v_readlane_b32 s12, v252, 40
	v_readlane_b32 s13, v252, 41
	v_lshlrev_b32_e32 v22, 7, v6
	v_mul_lo_u32 v8, v6, s14
	v_and_b32_e32 v32, -8, v4
	v_and_b32_e32 v34, -8, v6
	v_and_b32_e32 v36, -8, v9
	v_and_b32_e32 v38, -8, v11
	v_or_b32_e32 v53, s12, v214
	v_or_b32_e32 v6, s13, v214
	v_add_u32_e32 v54, s12, v214
	v_mul_u32_u24_e32 v17, 0x110, v214
	v_readlane_b32 s12, v254, 10
	s_add_u32 s20, s6, 0x1c8c2800
	v_lshlrev_b32_e32 v20, 7, v4
	v_mul_lo_u32 v7, v4, s14
	v_lshlrev_b32_e32 v24, 7, v9
	v_mul_lo_u32 v10, v9, s14
	v_lshlrev_b32_e32 v26, 7, v11
	v_mul_lo_u32 v12, v11, s14
	v_mul_lo_u32 v3, v32, s14
	v_mul_lo_u32 v14, v34, s14
	v_mul_lo_u32 v9, v36, s14
	v_mul_lo_u32 v11, v38, s14
	v_mul_u32_u24_e32 v15, 0x110, v53
	v_mul_u32_u24_e32 v0, 0x1b00, v53
	v_lshlrev_b32_e32 v2, 10, v53
	v_mul_u32_u24_e32 v16, 0x110, v6
	v_mul_u32_u24_e32 v4, 0x1b00, v6
	v_lshlrev_b32_e32 v6, 10, v6
	v_add3_u32 v55, v17, v215, s12
	v_readlane_b32 s12, v252, 7
	s_addc_u32 s21, s7, 0
	v_ashrrev_i32_e32 v21, 31, v20
	v_ashrrev_i32_e32 v23, 31, v22
	v_ashrrev_i32_e32 v25, 31, v24
	v_ashrrev_i32_e32 v27, 31, v26
	v_ashrrev_i32_e32 v33, 31, v32
	v_ashrrev_i32_e32 v35, 31, v34
	v_ashrrev_i32_e32 v37, 31, v36
	v_ashrrev_i32_e32 v39, 31, v38
	v_ashrrev_i32_e32 v41, 31, v40
	v_add3_u32 v56, v15, v215, 0
	v_add3_u32 v57, v16, v215, 0
	v_add_u32_e32 v58, v5, v7
	v_add_u32_e32 v59, v5, v8
	v_add_u32_e32 v60, v5, v10
	v_add_u32_e32 v61, v5, v12
	v_add_u32_e32 v62, v13, v3
	v_add_u32_e32 v63, v13, v14
	v_add_u32_e32 v64, v13, v9
	v_add_u32_e32 v65, v13, v11
	v_lshlrev_b32_e32 v42, 1, v0
	v_lshlrev_b32_e32 v44, 1, v2
	v_lshlrev_b32_e32 v0, 1, v4
	v_lshlrev_b32_e32 v46, 1, v6
	s_mov_b32 s22, s12
	v_readlane_b32 s13, v252, 8
